# phase 4: half of each XCD's workgroups run compress_task before post_tile so HBM-bound and L2-bound work overlap across workgroups
# baseline (speedup 1.0000x reference)
_Z8mega_fwd4Args:
	s_mov_b32 s101, 0
	s_load_dwordx8 s[84:91], s[0:1], 0x80
	s_load_dword s10, s[0:1], 0xa0
	s_add_u32 s4, s0, 0x98
	v_and_b32_e32 v175, 0x3ff, v0
	v_writelane_b32 v253, s2, 0
	s_addc_u32 s5, s1, 0
	s_getreg_b32 s11, hwreg(HW_REG_XCC_ID, 0, 4)
	v_cmp_gt_u32_e32 vcc, 2, v175
	s_and_saveexec_b64 s[2:3], vcc
	s_cbranch_execz .LBB0_2
	s_mov_b64 s[6:7], src_shared_base
	s_add_i32 s6, 0, 0x23fc0
	v_lshl_add_u32 v2, v175, 2, s6
	v_mov_b32_e32 v3, s7
	v_mov_b32_e32 v1, 0
	flat_store_dword v[2:3], v1 sc0 sc1
	s_waitcnt vmcnt(0)

.LBB0_280:
	s_cmp_eq_u32 s101, 1
	s_cbranch_scc0 .Lp4_latch
	s_mov_b32 s101, 2
	s_waitcnt vmcnt(0) lgkmcnt(0)
	s_barrier
	s_branch .Lp4_post
.Lp4_latch:
	s_mov_b32 s101, 0
	s_add_i32 s16, s16, s90
	v_readlane_b32 s0, v254, 22
	s_cmpk_gt_i32 s16, 0xff
	s_waitcnt lgkmcnt(0)
	v_add_u32_e32 v78, s0, v78
	s_barrier
	s_cbranch_scc1 .LBB0_619
.LBB0_281:
	s_cmp_eq_u32 s101, 0
	s_cbranch_scc0 .Lp4_post
	v_readlane_b32 s100, v253, 0
	s_bfe_u32 s100, s100, 0x10003
	s_cmp_eq_u32 s100, 1
	s_cbranch_scc0 .Lp4_post
	s_mov_b32 s101, 1
	s_branch .Lp4_cmp

.LBB0_548:
	v_add_u32_e32 v32, s0, v78
	v_add_u32_e32 v14, 8, v32
	v_mov_b64_e32 v[16:17], s[10:11]
	v_mad_i64_i32 v[18:19], s[2:3], v14, s23, v[16:17]
	v_mov_b32_e32 v9, v1
	v_lshl_add_u64 v[18:19], v[18:19], 0, v[8:9]
	global_load_dword v33, v[18:19], off offset:2608
	global_load_dword v53, v[18:19], off offset:3632
	v_add_co_u32_e32 v18, vcc, 0x1000, v18
	v_ashrrev_i32_e32 v15, 31, v14
	s_nop 0
	v_addc_co_u32_e32 v19, vcc, 0, v19, vcc
	global_load_dword v54, v[18:19], off offset:560
	v_add_u32_e32 v18, 9, v32
	v_mad_i64_i32 v[20:21], s[2:3], v18, s23, v[16:17]
	v_lshl_add_u64 v[20:21], v[20:21], 0, v[8:9]
	global_load_dword v55, v[20:21], off offset:2608
	global_load_dword v56, v[20:21], off offset:3632
	v_add_co_u32_e32 v20, vcc, 0x1000, v20
	v_ashrrev_i32_e32 v19, 31, v18
	s_nop 0
	v_addc_co_u32_e32 v21, vcc, 0, v21, vcc
	global_load_dword v57, v[20:21], off offset:560
	v_add_u32_e32 v20, 10, v32
	v_mad_i64_i32 v[22:23], s[2:3], v20, s23, v[16:17]
	v_lshl_add_u64 v[22:23], v[22:23], 0, v[8:9]
	global_load_dword v58, v[22:23], off offset:2608
	global_load_dword v59, v[22:23], off offset:3632
	v_add_co_u32_e32 v22, vcc, 0x1000, v22
	v_ashrrev_i32_e32 v21, 31, v20
	s_nop 0
	v_addc_co_u32_e32 v23, vcc, 0, v23, vcc
	global_load_dword v60, v[22:23], off offset:560
	v_add_u32_e32 v22, 11, v32
	v_mad_i64_i32 v[24:25], s[2:3], v22, s23, v[16:17]
	v_lshl_add_u64 v[24:25], v[24:25], 0, v[8:9]
	global_load_dword v61, v[24:25], off offset:2608
	global_load_dword v82, v[24:25], off offset:3632
	v_add_co_u32_e32 v24, vcc, 0x1000, v24
	v_ashrrev_i32_e32 v23, 31, v22
	s_nop 0
	v_addc_co_u32_e32 v25, vcc, 0, v25, vcc
	global_load_dword v83, v[24:25], off offset:560
	v_add_u32_e32 v24, 12, v32
	v_mad_i64_i32 v[26:27], s[2:3], v24, s23, v[16:17]
	v_lshl_add_u64 v[26:27], v[26:27], 0, v[8:9]
	global_load_dword v84, v[26:27], off offset:2608
	global_load_dword v85, v[26:27], off offset:3632
	v_add_co_u32_e32 v26, vcc, 0x1000, v26
	v_ashrrev_i32_e32 v25, 31, v24
	s_nop 0
	v_addc_co_u32_e32 v27, vcc, 0, v27, vcc
	global_load_dword v86, v[26:27], off offset:560
	v_add_u32_e32 v26, 13, v32
	v_mad_i64_i32 v[28:29], s[2:3], v26, s23, v[16:17]
	v_lshl_add_u64 v[28:29], v[28:29], 0, v[8:9]
	global_load_dword v87, v[28:29], off offset:2608
	global_load_dword v88, v[28:29], off offset:3632
	v_add_co_u32_e32 v28, vcc, 0x1000, v28
	v_ashrrev_i32_e32 v27, 31, v26
	s_nop 0
	v_addc_co_u32_e32 v29, vcc, 0, v29, vcc
	global_load_dword v89, v[28:29], off offset:560
	v_add_u32_e32 v28, 14, v32
	v_mad_i64_i32 v[30:31], s[2:3], v28, s23, v[16:17]
	v_lshl_add_u64 v[30:31], v[30:31], 0, v[8:9]
	global_load_dword v90, v[30:31], off offset:2608
	global_load_dword v91, v[30:31], off offset:3632
	v_add_co_u32_e32 v30, vcc, 0x1000, v30
	v_ashrrev_i32_e32 v29, 31, v28
	s_nop 0
	v_addc_co_u32_e32 v31, vcc, 0, v31, vcc
	global_load_dword v92, v[30:31], off offset:560
	v_add_u32_e32 v30, 15, v32
	v_mad_i64_i32 v[16:17], s[2:3], v30, s23, v[16:17]
	v_lshl_add_u64 v[16:17], v[16:17], 0, v[8:9]
	global_load_dword v93, v[16:17], off offset:2608
	global_load_dword v94, v[16:17], off offset:3632
	v_add_co_u32_e32 v16, vcc, 0x1000, v16
	s_waitcnt vmcnt(22)
	v_lshlrev_b32_e32 v32, 16, v33
	v_addc_co_u32_e32 v17, vcc, 0, v17, vcc
	global_load_dword v95, v[16:17], off offset:560
	v_and_b32_e32 v33, 0xffff0000, v33
	v_ashrrev_i32_e32 v31, 31, v30
	s_waitcnt vmcnt(21)
	v_lshlrev_b32_e32 v16, 16, v54
	v_and_b32_e32 v17, 0xffff0000, v54
	v_pk_mul_f32 v[16:17], v[32:33], v[16:17]
	s_add_i32 s0, s0, 8
	v_pk_mul_f32 v[32:33], v[6:7], v[16:17]
	s_cmp_lt_u32 s0, 24
	v_pk_fma_f32 v[32:33], v[4:5], v[10:11], v[32:33]
	s_nop 0
	v_pk_fma_f32 v[12:13], v[2:3], v[12:13], v[32:33]
	v_lshlrev_b32_e32 v32, 16, v53
	v_and_b32_e32 v33, 0xffff0000, v53
	v_pk_mul_f32 v[12:13], v[12:13], v[32:33]
	s_nop 0
	v_cvt_pk_bf16_f32 v32, v12, v13
	v_lshlrev_b64 v[12:13], 11, v[14:15]
	v_lshl_add_u64 v[12:13], s[4:5], 0, v[12:13]
	v_lshl_add_u64 v[12:13], v[12:13], 0, v[8:9]
	v_add_co_u32_e32 v12, vcc, s91, v12
	s_waitcnt vmcnt(20)
	v_lshlrev_b32_e32 v14, 16, v55
	v_addc_co_u32_e32 v13, vcc, 0, v13, vcc
	global_store_dword v[12:13], v32, off offset:1024
	s_waitcnt vmcnt(19)
	v_lshlrev_b32_e32 v12, 16, v57
	v_and_b32_e32 v13, 0xffff0000, v57
	v_and_b32_e32 v15, 0xffff0000, v55
	v_pk_mul_f32 v[12:13], v[14:15], v[12:13]
	s_nop 0
	v_pk_mul_f32 v[14:15], v[6:7], v[12:13]
	s_nop 0
	v_pk_fma_f32 v[14:15], v[4:5], v[16:17], v[14:15]
	s_nop 0
	v_pk_fma_f32 v[10:11], v[2:3], v[10:11], v[14:15]
	v_lshlrev_b32_e32 v14, 16, v56
	v_and_b32_e32 v15, 0xffff0000, v56
	v_pk_mul_f32 v[10:11], v[10:11], v[14:15]
	s_waitcnt vmcnt(18)
	v_and_b32_e32 v15, 0xffff0000, v58
	v_cvt_pk_bf16_f32 v14, v10, v11
	v_lshlrev_b64 v[10:11], 11, v[18:19]
	v_lshl_add_u64 v[10:11], s[4:5], 0, v[10:11]
	v_lshl_add_u64 v[10:11], v[10:11], 0, v[8:9]
	v_add_co_u32_e32 v10, vcc, s91, v10
	s_nop 1
	v_addc_co_u32_e32 v11, vcc, 0, v11, vcc
	global_store_dword v[10:11], v14, off offset:1024
	s_waitcnt vmcnt(17)
	v_lshlrev_b32_e32 v10, 16, v60
	v_lshlrev_b32_e32 v14, 16, v58
	v_and_b32_e32 v11, 0xffff0000, v60
	v_pk_mul_f32 v[10:11], v[14:15], v[10:11]
	s_nop 0
	v_pk_mul_f32 v[14:15], v[6:7], v[10:11]
	s_nop 0
	v_pk_fma_f32 v[14:15], v[4:5], v[12:13], v[14:15]
	s_nop 0
	v_pk_fma_f32 v[14:15], v[2:3], v[16:17], v[14:15]
	v_lshlrev_b32_e32 v16, 16, v59
	v_and_b32_e32 v17, 0xffff0000, v59
	v_pk_mul_f32 v[14:15], v[14:15], v[16:17]
	s_waitcnt vmcnt(16)
	v_and_b32_e32 v17, 0xffff0000, v61
	v_cvt_pk_bf16_f32 v16, v14, v15
	v_lshlrev_b64 v[14:15], 11, v[20:21]
	v_lshl_add_u64 v[14:15], s[4:5], 0, v[14:15]
	v_lshl_add_u64 v[14:15], v[14:15], 0, v[8:9]
	v_add_co_u32_e32 v14, vcc, s91, v14
	s_nop 1
	v_addc_co_u32_e32 v15, vcc, 0, v15, vcc
	global_store_dword v[14:15], v16, off offset:1024
	s_waitcnt vmcnt(15)
	v_lshlrev_b32_e32 v14, 16, v83
	v_lshlrev_b32_e32 v16, 16, v61
	v_and_b32_e32 v15, 0xffff0000, v83
	v_pk_mul_f32 v[14:15], v[16:17], v[14:15]
	s_nop 0
	v_pk_mul_f32 v[16:17], v[6:7], v[14:15]
	s_nop 0
	v_pk_fma_f32 v[16:17], v[4:5], v[10:11], v[16:17]
	s_nop 0
	v_pk_fma_f32 v[12:13], v[2:3], v[12:13], v[16:17]
	v_lshlrev_b32_e32 v16, 16, v82
	v_and_b32_e32 v17, 0xffff0000, v82
	v_pk_mul_f32 v[12:13], v[12:13], v[16:17]
	s_waitcnt vmcnt(14)
	v_and_b32_e32 v17, 0xffff0000, v84
	v_cvt_pk_bf16_f32 v16, v12, v13
	v_lshlrev_b64 v[12:13], 11, v[22:23]
	v_lshl_add_u64 v[12:13], s[4:5], 0, v[12:13]
	v_lshl_add_u64 v[12:13], v[12:13], 0, v[8:9]
	v_add_co_u32_e32 v12, vcc, s91, v12
	s_nop 1
	v_addc_co_u32_e32 v13, vcc, 0, v13, vcc
	global_store_dword v[12:13], v16, off offset:1024
	s_waitcnt vmcnt(13)
	v_lshlrev_b32_e32 v12, 16, v86
	v_lshlrev_b32_e32 v16, 16, v84
	v_and_b32_e32 v13, 0xffff0000, v86
	v_pk_mul_f32 v[16:17], v[16:17], v[12:13]
	s_nop 0
	v_pk_mul_f32 v[12:13], v[6:7], v[16:17]
	s_nop 0
	v_pk_fma_f32 v[12:13], v[4:5], v[14:15], v[12:13]
	s_nop 0
	v_pk_fma_f32 v[10:11], v[2:3], v[10:11], v[12:13]
	v_lshlrev_b32_e32 v12, 16, v85
	v_and_b32_e32 v13, 0xffff0000, v85
	v_pk_mul_f32 v[10:11], v[10:11], v[12:13]
	s_waitcnt vmcnt(12)
	v_and_b32_e32 v13, 0xffff0000, v87
	v_cvt_pk_bf16_f32 v12, v10, v11
	v_lshlrev_b64 v[10:11], 11, v[24:25]
	v_lshl_add_u64 v[10:11], s[4:5], 0, v[10:11]
	v_lshl_add_u64 v[10:11], v[10:11], 0, v[8:9]
	v_add_co_u32_e32 v10, vcc, s91, v10
	s_nop 1
	v_addc_co_u32_e32 v11, vcc, 0, v11, vcc
	global_store_dword v[10:11], v12, off offset:1024
	s_waitcnt vmcnt(11)
	v_lshlrev_b32_e32 v10, 16, v89
	v_lshlrev_b32_e32 v12, 16, v87
	v_and_b32_e32 v11, 0xffff0000, v89
	v_pk_mul_f32 v[18:19], v[12:13], v[10:11]
	v_lshlrev_b32_e32 v12, 16, v88
	v_pk_mul_f32 v[10:11], v[6:7], v[18:19]
	v_and_b32_e32 v13, 0xffff0000, v88
	v_pk_fma_f32 v[10:11], v[4:5], v[16:17], v[10:11]
	s_nop 0
	v_pk_fma_f32 v[10:11], v[2:3], v[14:15], v[10:11]
	s_waitcnt vmcnt(9)
	v_lshlrev_b32_e32 v14, 16, v91
	v_pk_mul_f32 v[10:11], v[10:11], v[12:13]
	v_and_b32_e32 v13, 0xffff0000, v90
	v_cvt_pk_bf16_f32 v12, v10, v11
	v_lshlrev_b64 v[10:11], 11, v[26:27]
	v_lshl_add_u64 v[10:11], s[4:5], 0, v[10:11]
	v_lshl_add_u64 v[10:11], v[10:11], 0, v[8:9]
	v_add_co_u32_e32 v10, vcc, s91, v10
	v_and_b32_e32 v15, 0xffff0000, v91
	s_nop 0
	v_addc_co_u32_e32 v11, vcc, 0, v11, vcc
	global_store_dword v[10:11], v12, off offset:1024
	s_waitcnt vmcnt(9)
	v_lshlrev_b32_e32 v10, 16, v92
	v_lshlrev_b32_e32 v12, 16, v90
	v_and_b32_e32 v11, 0xffff0000, v92
	v_pk_mul_f32 v[12:13], v[12:13], v[10:11]
	s_nop 0
	v_pk_mul_f32 v[10:11], v[6:7], v[12:13]
	s_nop 0
	v_pk_fma_f32 v[10:11], v[4:5], v[18:19], v[10:11]
	s_nop 0
	v_pk_fma_f32 v[10:11], v[2:3], v[16:17], v[10:11]
	s_waitcnt vmcnt(7)
	v_lshlrev_b32_e32 v16, 16, v94
	v_pk_mul_f32 v[10:11], v[10:11], v[14:15]
	v_and_b32_e32 v15, 0xffff0000, v93
	v_cvt_pk_bf16_f32 v14, v10, v11
	v_lshlrev_b64 v[10:11], 11, v[28:29]
	v_lshl_add_u64 v[10:11], s[4:5], 0, v[10:11]
	v_lshl_add_u64 v[10:11], v[10:11], 0, v[8:9]
	v_add_co_u32_e32 v10, vcc, s91, v10
	v_and_b32_e32 v17, 0xffff0000, v94
	s_nop 0
	v_addc_co_u32_e32 v11, vcc, 0, v11, vcc
	global_store_dword v[10:11], v14, off offset:1024
	s_waitcnt vmcnt(7)
	v_lshlrev_b32_e32 v10, 16, v95
	v_lshlrev_b32_e32 v14, 16, v93
	v_and_b32_e32 v11, 0xffff0000, v95
	v_pk_mul_f32 v[10:11], v[14:15], v[10:11]
	s_nop 0
	v_pk_mul_f32 v[14:15], v[6:7], v[10:11]
	s_nop 0
	v_pk_fma_f32 v[14:15], v[4:5], v[12:13], v[14:15]
	s_nop 0
	v_pk_fma_f32 v[14:15], v[2:3], v[18:19], v[14:15]
	s_nop 0
	v_pk_mul_f32 v[14:15], v[14:15], v[16:17]
	s_nop 0
	v_cvt_pk_bf16_f32 v16, v14, v15
	v_lshlrev_b64 v[14:15], 11, v[30:31]
	v_lshl_add_u64 v[14:15], s[4:5], 0, v[14:15]
	v_lshl_add_u64 v[14:15], v[14:15], 0, v[8:9]
	v_add_co_u32_e32 v14, vcc, 0xd000000, v14
	s_nop 1
	v_addc_co_u32_e32 v15, vcc, 0, v15, vcc
	global_store_dword v[14:15], v16, off offset:1024
	s_cbranch_scc1 .LBB0_548
	s_cmp_eq_u32 s101, 2
	s_cbranch_scc1 .LBB0_280
.Lp4_cmp:
	s_and_b32 s2, s16, 0xffffff80
	s_lshl_b32 s3, s16, 4
	s_and_b32 s12, s3, 0x1f0
	s_ashr_i32 s3, s2, 31
	s_lshr_b32 s6, s16, 6
	s_bfe_u32 s0, s16, 0x10006
	s_lshl_b64 s[8:9], s[2:3], 1
	s_add_u32 s3, s7, s8
	s_addc_u32 s9, s26, s9
	s_lshl_b32 s8, s16, 1
	v_or_b32_e32 v2, s2, v71
	s_and_b32 s17, s8, 64
	v_ashrrev_i32_e32 v3, 31, v2
	s_lshl_b32 s8, s17, 1
	v_lshlrev_b64 v[2:3], 12, v[2:3]
	s_add_u32 s8, s3, s8
	v_lshl_add_u64 v[54:55], v[50:51], 0, v[2:3]
	s_addc_u32 s9, s9, 0
	v_mov_b32_e32 v53, v1
	v_or_b32_e32 v2, s12, v71
	v_lshl_add_u64 v[56:57], s[8:9], 0, v[52:53]
	v_lshlrev_b32_e32 v53, 4, v2
	v_mov_b32_e32 v2, 0
	s_lshl_b32 s3, s0, 13
	s_mov_b64 s[8:9], 0
	v_mov_b32_e32 v58, v72
	v_mov_b32_e32 v3, v2
	v_mov_b32_e32 v4, v2
	v_mov_b32_e32 v5, v2
	v_mov_b32_e32 v6, v2
	v_mov_b32_e32 v7, v2
	v_mov_b32_e32 v8, v2
	v_mov_b32_e32 v9, v2
	v_mov_b32_e32 v10, v2
	v_mov_b32_e32 v11, v2
	v_mov_b32_e32 v12, v2
	v_mov_b32_e32 v13, v2
	v_mov_b32_e32 v14, v2
	v_mov_b32_e32 v15, v2
	v_mov_b32_e32 v16, v2
	v_mov_b32_e32 v17, v2
	v_mov_b32_e32 v18, v2
	v_mov_b32_e32 v19, v2
	v_mov_b32_e32 v20, v2
	v_mov_b32_e32 v21, v2
	v_mov_b32_e32 v22, v2
	v_mov_b32_e32 v23, v2
	v_mov_b32_e32 v24, v2
	v_mov_b32_e32 v25, v2
	v_mov_b32_e32 v26, v2
	v_mov_b32_e32 v27, v2
	v_mov_b32_e32 v28, v2
	v_mov_b32_e32 v29, v2
	v_mov_b32_e32 v30, v2
	v_mov_b32_e32 v31, v2
	v_mov_b32_e32 v32, v2
	v_mov_b32_e32 v33, v2
	s_barrier

	.amdhsa_kernel _Z8mega_fwd4Args
		.amdhsa_group_segment_fixed_size 0
		.amdhsa_private_segment_fixed_size 0
		.amdhsa_kernarg_size 408
		.amdhsa_user_sgpr_count 2
		.amdhsa_user_sgpr_dispatch_ptr 0
		.amdhsa_user_sgpr_queue_ptr 0
		.amdhsa_user_sgpr_kernarg_segment_ptr 1
		.amdhsa_user_sgpr_dispatch_id 0
		.amdhsa_user_sgpr_kernarg_preload_length 0
		.amdhsa_user_sgpr_kernarg_preload_offset 0
		.amdhsa_user_sgpr_private_segment_size 0
		.amdhsa_uses_dynamic_stack 0
		.amdhsa_enable_private_segment 0
		.amdhsa_system_sgpr_workgroup_id_x 1
		.amdhsa_system_sgpr_workgroup_id_y 0
		.amdhsa_system_sgpr_workgroup_id_z 0
		.amdhsa_system_sgpr_workgroup_info 0
		.amdhsa_system_vgpr_workitem_id 2
		.amdhsa_next_free_vgpr 256
		.amdhsa_next_free_sgpr 102
		.amdhsa_accum_offset 256
		.amdhsa_reserve_vcc 1
		.amdhsa_float_round_mode_32 0
		.amdhsa_float_round_mode_16_64 0
		.amdhsa_float_denorm_mode_32 3
		.amdhsa_float_denorm_mode_16_64 3
		.amdhsa_dx10_clamp 1
		.amdhsa_ieee_mode 1
		.amdhsa_fp16_overflow 0
		.amdhsa_tg_split 0
		.amdhsa_exception_fp_ieee_invalid_op 0
		.amdhsa_exception_fp_denorm_src 0
		.amdhsa_exception_fp_ieee_div_zero 0
		.amdhsa_exception_fp_ieee_overflow 0
		.amdhsa_exception_fp_ieee_underflow 0
		.amdhsa_exception_fp_ieee_inexact 0
		.amdhsa_exception_int_div_zero 0
	.end_amdhsa_kernel

amdhsa.kernels:
  - .agpr_count:     0
    .args:
      - .offset:         0
        .size:           152
        .value_kind:     by_value
      - .offset:         152
        .size:           4
        .value_kind:     hidden_block_count_x
      - .offset:         156
        .size:           4
        .value_kind:     hidden_block_count_y
      - .offset:         160
        .size:           4
        .value_kind:     hidden_block_count_z
      - .offset:         164
        .size:           2
        .value_kind:     hidden_group_size_x
      - .offset:         166
        .size:           2
        .value_kind:     hidden_group_size_y
      - .offset:         168
        .size:           2
        .value_kind:     hidden_group_size_z
      - .offset:         170
        .size:           2
        .value_kind:     hidden_remainder_x
      - .offset:         172
        .size:           2
        .value_kind:     hidden_remainder_y
      - .offset:         174
        .size:           2
        .value_kind:     hidden_remainder_z
      - .offset:         192
        .size:           8
        .value_kind:     hidden_global_offset_x
      - .offset:         200
        .size:           8
        .value_kind:     hidden_global_offset_y
      - .offset:         208
        .size:           8
        .value_kind:     hidden_global_offset_z
      - .offset:         216
        .size:           2
        .value_kind:     hidden_grid_dims
      - .offset:         240
        .size:           8
        .value_kind:     hidden_multigrid_sync_arg
      - .offset:         272
        .size:           4
        .value_kind:     hidden_dynamic_lds_size
    .group_segment_fixed_size: 0
    .kernarg_segment_align: 8
    .kernarg_segment_size: 408
    .language:       OpenCL C
    .language_version:
      - 2
      - 0
    .max_flat_workgroup_size: 512
    .name:           _Z8mega_fwd4Args
    .private_segment_fixed_size: 0
    .sgpr_count:     108
    .sgpr_spill_count: 201
    .symbol:         _Z8mega_fwd4Args.kd
    .uniform_work_group_size: 1
    .uses_dynamic_stack: false
    .vgpr_count:     256
    .vgpr_spill_count: 0
    .wavefront_size: 64
